# one static s_setprio 1 for waves 4-7 across both attention unit loops, reset at loop exit (on keep_v7)
# speedup vs baseline: 1.0006x; 1.0006x over previous
.LBB0_283:
	v_readlane_b32 s98, v255, 0
	s_nop 3
	s_cmp_lt_u32 s98, 0x100
	s_cbranch_scc1 .Lprio_l1
	s_setprio 1

.LBB0_301:
	s_setprio 0
	s_mov_b64 s[2:3], 0

.LBB0_617:
	s_setprio 0
	s_mov_b64 s[4:5], s[0:1]
	v_mbcnt_lo_u32_b32 v0, -1, 0
	v_mbcnt_hi_u32_b32 v0, -1, v0
	s_waitcnt vmcnt(0)
	v_readlane_b32 s2, v255, 2
	s_waitcnt lgkmcnt(0)
	s_barrier
	v_cmp_eq_u32_e32 vcc, s2, v0
	s_and_saveexec_b64 s[2:3], vcc
	s_cbranch_execz .LBB0_669
	v_readlane_b32 s7, v255, 52
	s_load_dwordx2 s[4:5], s[4:5], 0x128
	s_getreg_b32 s6, hwreg(HW_REG_XCC_ID, 0, 4)
	v_mov_b32_e32 v0, s7
	s_waitcnt vmcnt(0) expcnt(0) lgkmcnt(0)
	ds_read_b32 v3, v0
	v_readlane_b32 s7, v255, 53
	s_and_b32 s9, s6, 15
	s_waitcnt lgkmcnt(0)
	v_cmp_ne_u32_e32 vcc, 0, v3
	v_mov_b32_e32 v0, s7
	ds_read_b32 v2, v0
	s_cbranch_vccnz .LBB0_633
	s_add_u32 s6, s4, 0x300200
	s_addc_u32 s7, s5, 0
	s_add_u32 s12, s4, 0x300400
	s_addc_u32 s13, s5, 0
	s_add_u32 s14, s4, 0x300500
	s_addc_u32 s15, s5, 0
	s_add_u32 s16, s4, 0x300600
	s_addc_u32 s17, s5, 0
	s_add_u32 s18, s4, 0x300700
	s_addc_u32 s19, s5, 0
	s_add_u32 s22, s4, 0x300800
	s_addc_u32 s23, s5, 0
	s_add_u32 s24, s4, 0x300900
	s_addc_u32 s25, s5, 0
	s_add_u32 s26, s4, 0x300a00
	s_addc_u32 s27, s5, 0
	s_add_u32 s36, s4, 0x300b00
	s_addc_u32 s37, s5, 0
	s_add_u32 s38, s4, 0x300c00
	s_addc_u32 s39, s5, 0
	s_add_u32 s60, s4, 0x300d00
	s_addc_u32 s61, s5, 0
	s_add_u32 s72, s4, 0x300e00
	s_addc_u32 s73, s5, 0
	s_add_u32 s28, s4, 0x300f00
	s_addc_u32 s29, s5, 0
	s_add_u32 s40, s4, 0x301000
	s_addc_u32 s41, s5, 0
	s_add_u32 s42, s4, 0x301100
	s_addc_u32 s43, s5, 0
	s_add_u32 s44, s4, 0x301200
	s_addc_u32 s45, s5, 0
	s_add_u32 s46, s4, 0x301300
	s_addc_u32 s47, s5, 0
	s_mov_b32 s20, 1
	s_branch .LBB0_621
